# row-stat exchange poll loop sleeps longer between polls (s_sleep 12)
# speedup vs baseline: 1.0006x; 1.0006x over previous
.LBB0_899:
	s_or_b64 exec, exec, s[44:45]
	v_cndmask_b32_e64 v10, 0, 1, s[46:47]
	v_cmp_ne_u32_e32 vcc, 0, v10
	s_cbranch_vccz .LBB0_896
	s_memrealtime s[6:7]
	s_waitcnt lgkmcnt(0)
	s_sub_u32 s6, s6, s12
	s_subb_u32 s7, s7, s13
	v_cmp_lt_u64_e32 vcc, s[6:7], v[252:253]
	s_cbranch_vccz .LBB0_896
	s_mov_b64 s[42:43], 0
	s_sleep 12
	s_branch .LBB0_896
